# prompt attention: K tiles fetched by LDS-DMA (64-byte coalesced segments, XOR-swizzled) and read as ds_read_b128 fragments instead of per-lane strided 16-byte global loads; K and V single-buffered per
# speedup vs baseline: 1.0925x; 1.0225x over previous
.LBB0_1123:
	s_lshl_b32 s0, s28, 14
	s_add_i32 s90, s0, 0
	s_add_u32 s0, s14, 0x6088300
	v_writelane_b32 v255, s0, 37
	s_addc_u32 s0, s15, 0
	v_writelane_b32 v255, s0, 38
	s_add_u32 s0, s14, 0x10128300
	v_writelane_b32 v255, s0, 39
	s_addc_u32 s0, s15, 0
	v_writelane_b32 v255, s0, 40
	s_add_u32 s0, s14, 0x16128300
	v_writelane_b32 v255, s0, 41
	s_addc_u32 s0, s15, 0
	v_writelane_b32 v255, s0, 42
	s_add_u32 s0, s14, 0x8088300
	v_lshrrev_b32_e32 v1, 5, v81
	v_writelane_b32 v255, s0, 43
	s_addc_u32 s0, s15, 0
	v_writelane_b32 v255, s0, 44
	s_add_u32 s0, s14, 0xa088300
	v_lshlrev_b32_e32 v4, 3, v1
	v_lshlrev_b32_e32 v1, 2, v1
	v_and_b32_e32 v157, 31, v98
	v_writelane_b32 v255, s0, 45
	s_addc_u32 s0, s15, 0
	v_lshrrev_b32_e32 v158, 2, v81
	v_or_b32_e32 v6, 1, v1
	v_writelane_b32 v255, s0, 46
	v_lshlrev_b32_e32 v0, 3, v81
	v_and_or_b32 v3, v158, 3, v1
	v_cmp_lt_u32_e64 s[4:5], v1, v157
	v_cmp_lt_u32_e64 s[6:7], v6, v157
	v_or_b32_e32 v6, 2, v1
	v_or_b32_e32 v7, 3, v1
	v_or_b32_e32 v8, 8, v1
	v_or_b32_e32 v9, 9, v1
	s_waitcnt vmcnt(5)
	v_or_b32_e32 v10, 10, v1
	v_or_b32_e32 v11, 11, v1
	v_or_b32_e32 v12, 16, v1
	v_or_b32_e32 v13, 17, v1
	s_waitcnt vmcnt(4)
	v_or_b32_e32 v14, 18, v1
	v_or_b32_e32 v15, 19, v1
	v_or_b32_e32 v16, 24, v1
	v_or_b32_e32 v17, 25, v1
	s_waitcnt vmcnt(3)
	v_or_b32_e32 v18, 26, v1
	v_or_b32_e32 v19, 27, v1
	v_cmp_gt_u32_e64 s[38:39], v1, v157
	v_mov_b32_e32 v1, s90
	s_movk_i32 s0, 0x110
	v_and_b32_e32 v0, 24, v0
	v_lshlrev_b32_e32 v5, 1, v81
	v_mad_u32_u24 v1, v157, s0, v1
	v_cmp_gt_u32_e64 s[0:1], 32, v81
	v_and_b32_e32 v2, 8, v158
	v_lshlrev_b32_e32 v3, 6, v3
	v_cmp_lt_u32_e64 s[8:9], v6, v157
	v_cmp_lt_u32_e64 s[10:11], v7, v157
	v_cmp_gt_u32_e64 s[40:41], v6, v157
	v_cmp_gt_u32_e64 s[42:43], v7, v157
	v_lshl_add_u32 v6, v83, 4, s90
	v_mul_u32_u24_e32 v7, 0x110, v156
	v_writelane_b32 v255, s0, 47
	v_and_or_b32 v5, v5, 32, v0
	s_mov_b32 s69, s84
	v_cmp_lt_u32_e64 s[12:13], v8, v157
	v_cmp_lt_u32_e64 s[14:15], v9, v157
	v_cmp_lt_u32_e64 s[16:17], v10, v157
	v_cmp_lt_u32_e64 s[18:19], v11, v157
	v_cmp_lt_u32_e64 s[20:21], v12, v157
	v_cmp_lt_u32_e64 s[22:23], v13, v157
	v_cmp_lt_u32_e64 s[24:25], v14, v157
	v_cmp_lt_u32_e64 s[26:27], v15, v157
	v_cmp_lt_u32_e64 s[28:29], v16, v157
	v_cmp_lt_u32_e64 s[30:31], v17, v157
	v_cmp_lt_u32_e64 s[34:35], v18, v157
	v_cmp_lt_u32_e64 s[36:37], v19, v157
	v_cmp_gt_u32_e64 s[44:45], v8, v157
	v_cmp_gt_u32_e64 s[46:47], v9, v157
	v_cmp_gt_u32_e64 s[48:49], v10, v157
	v_cmp_gt_u32_e64 s[50:51], v11, v157
	v_cmp_gt_u32_e64 s[52:53], v12, v157
	v_cmp_gt_u32_e64 s[54:55], v13, v157
	v_cmp_gt_u32_e64 s[56:57], v14, v157
	v_cmp_gt_u32_e64 s[58:59], v15, v157
	v_cmp_gt_u32_e64 s[60:61], v16, v157
	v_cmp_gt_u32_e64 s[62:63], v17, v157
	v_cmp_gt_u32_e64 s[64:65], v18, v157
	v_cmp_gt_u32_e64 s[66:67], v19, v157
	v_or_b32_e32 v159, 4, v156
	v_or_b32_e32 v160, 8, v156
	v_or_b32_e32 v161, 12, v156
	v_or_b32_e32 v162, 16, v156
	v_or_b32_e32 v163, 20, v156
	v_or_b32_e32 v164, 24, v156
	v_or_b32_e32 v165, 28, v156
	v_writelane_b32 v255, s1, 48
	v_add3_u32 v166, v3, s90, v5
	v_or_b32_e32 v167, 0xffffffa0, v157
	v_or_b32_e32 v168, 0xffffffa0, v158
	v_lshlrev_b32_e32 v188, 1, v0
	v_lshlrev_b32_e32 v144, 1, v2
	v_lshlrev_b32_e32 v146, 1, v4
	v_add_u32_e32 v169, v1, v4
	v_lshlrev_b32_e32 v148, 1, v80
	v_add_u32_e32 v170, v6, v7
	v_bfe_u32 v200, v157, 2, 2
	v_lshrrev_b32_e32 v201, 5, v81
	v_xor_b32_e32 v202, v201, v200
	v_or_b32_e32 v203, 2, v201
	v_xor_b32_e32 v203, v203, v200
	v_lshlrev_b32_e32 v204, 6, v157
	v_add_u32_e32 v204, s90, v204
	v_lshl_add_u32 v196, v202, 4, v204
	v_lshl_add_u32 v197, v203, 4, v204
	v_and_b32_e32 v198, 3, v81
	v_bfe_u32 v199, v81, 4, 2
	v_xor_b32_e32 v198, v198, v199
	v_lshlrev_b32_e32 v198, 4, v198
	v_mov_b32_e32 v199, 0
	s_mov_b64 s[100:101], 0xc0
	s_branch .LBB0_1125

.LBB0_1133:
	s_lshl_b32 s0, s2, 3
	v_readlane_b32 s1, v255, 36
	s_or_b32 s3, s0, s1
	v_readlane_b32 s0, v255, 34
	v_readlane_b32 s1, v255, 35
	s_and_b64 s[0:1], s[0:1], exec
	s_cselect_b32 s82, s3, s2
	s_ashr_i32 s83, s82, 31
	s_lshl_b64 s[70:71], s[82:83], 19
	s_lshl_b64 s[78:79], s[82:83], 20
	v_readlane_b32 s0, v255, 37
	s_add_u32 s0, s0, s78
	v_readlane_b32 s1, v255, 38
	s_addc_u32 s1, s1, s79
	v_readlane_b32 s2, v255, 43
	s_add_u32 s2, s2, s78
	v_readlane_b32 s3, v255, 44
	v_add_u32_e32 v2, s73, v157
	s_addc_u32 s3, s3, s79
	v_readlane_b32 s76, v255, 45
	v_ashrrev_i32_e32 v0, 31, v2
	s_add_u32 vcc_lo, s76, s78
	v_readlane_b32 s76, v255, 46
	v_mul_lo_u32 v3, s74, v0
	v_mov_b64_e32 v[0:1], s[84:85]
	s_addc_u32 vcc_hi, s76, s79
	v_mad_u64_u32 v[150:151], s[78:79], s74, v2, v[0:1]
	s_sub_i32 s78, 0x80, s73
	s_lshr_b32 s78, s78, 5
	s_cmpk_lt_i32 s73, 0x80
	s_cselect_b32 s81, s78, 0
	s_lshl_b32 s78, s81, 5
	s_add_i32 s76, s78, s73
	s_add_i32 s94, s76, 0xffffff80
	v_mul_lo_u32 v0, s75, v2
	v_add_u32_e32 v2, s94, v158
	v_add3_u32 v151, v0, v151, v3
	v_ashrrev_i32_e32 v0, 31, v2
	v_mul_lo_u32 v3, s74, v0
	v_mov_b64_e32 v[0:1], s[84:85]
	v_mul_lo_u32 v4, s75, v2
	v_mad_u64_u32 v[0:1], s[78:79], s74, v2, v[0:1]
	v_add3_u32 v1, v4, v1, v3
	v_lshlrev_b64 v[0:1], 8, v[0:1]
	v_lshl_add_u64 v[0:1], vcc, 0, v[0:1]
	s_add_i32 m0, s90, 0x2000
	v_lshl_add_u64 v[0:1], v[0:1], 0, v[188:189]
	s_lshl_b64 s[96:97], s[74:75], 12
	global_load_lds_dwordx4 v[0:1], off
	v_lshl_add_u64 v[2:3], v[0:1], 0, s[96:97]
	s_add_i32 m0, s90, 0x2400
	v_lshl_add_u64 v[4:5], v[0:1], 0, 64
	global_load_lds_dwordx4 v[2:3], off
	s_add_i32 m0, s90, 0x2800
	s_mov_b64 s[78:79], 0xc0
	global_load_lds_dwordx4 v[4:5], off
	v_lshl_add_u64 v[4:5], v[2:3], 0, 64
	s_add_i32 m0, s90, 0x2c00
	v_mov_b32_e32 v145, v189
	global_load_lds_dwordx4 v[4:5], off
	v_lshl_add_u64 v[4:5], v[0:1], 0, s[88:89]
	s_add_i32 m0, s90, 0x3000
	v_lshl_add_u64 v[0:1], v[0:1], 0, s[78:79]
	global_load_lds_dwordx4 v[4:5], off
	v_lshl_add_u64 v[4:5], v[2:3], 0, s[88:89]
	s_add_i32 m0, s90, 0x3400
	v_mov_b32_e32 v147, v189
	global_load_lds_dwordx4 v[4:5], off
	s_add_i32 m0, s90, 0x3800
	v_mov_b32_e32 v14, v189
	global_load_lds_dwordx4 v[0:1], off
	v_lshl_add_u64 v[0:1], v[2:3], 0, s[78:79]
	s_add_i32 m0, s90, 0x3c00
	s_nop 0
	global_load_lds_dwordx4 v[0:1], off
	v_add_u32_e32 v2, s94, v158
	v_ashrrev_i32_e32 v116, 31, v2
	v_mov_b64_e32 v[112:113], s[84:85]
	v_mad_u64_u32 v[114:115], s[78:79], s74, v2, v[112:113]
	v_mul_lo_u32 v117, s75, v2
	v_mul_lo_u32 v116, s74, v116
	v_add3_u32 v115, v117, v115, v116
	v_lshlrev_b64 v[114:115], 8, v[114:115]
	v_lshl_add_u64 v[114:115], s[2:3], 0, v[114:115]
	v_lshl_add_u64 v[114:115], v[114:115], 0, v[198:199]
	s_mov_b32 m0, s90
	v_lshl_add_u64 v[116:117], v[114:115], 0, s[96:97]
	global_load_lds_dwordx4 v[114:115], off
	s_add_i32 m0, s90, 0x400
	v_lshl_add_u64 v[118:119], v[114:115], 0, 64
	global_load_lds_dwordx4 v[116:117], off
	s_add_i32 m0, s90, 0x800
	s_nop 0
	global_load_lds_dwordx4 v[118:119], off
	v_lshl_add_u64 v[118:119], v[116:117], 0, 64
	s_add_i32 m0, s90, 0xc00
	s_nop 0
	global_load_lds_dwordx4 v[118:119], off
	v_lshl_add_u64 v[118:119], v[114:115], 0, s[88:89]
	s_add_i32 m0, s90, 0x1000
	v_lshl_add_u64 v[114:115], v[114:115], 0, s[100:101]
	global_load_lds_dwordx4 v[118:119], off
	v_lshl_add_u64 v[118:119], v[116:117], 0, s[88:89]
	s_add_i32 m0, s90, 0x1400
	s_nop 0
	global_load_lds_dwordx4 v[118:119], off
	s_add_i32 m0, s90, 0x1800
	s_nop 0
	global_load_lds_dwordx4 v[114:115], off
	v_lshl_add_u64 v[114:115], v[116:117], 0, s[100:101]
	s_add_i32 m0, s90, 0x1c00
	s_nop 0
	global_load_lds_dwordx4 v[114:115], off
	v_lshlrev_b64 v[0:1], 8, v[150:151]
	v_lshl_add_u64 v[0:1], s[0:1], 0, v[0:1]
	v_lshl_add_u64 v[0:1], v[0:1], 0, v[146:147]
	global_load_dwordx4 v[80:83], v[0:1], off
	global_load_dwordx4 v[84:87], v[0:1], off offset:32
	global_load_dwordx4 v[88:91], v[0:1], off offset:64
	global_load_dwordx4 v[92:95], v[0:1], off offset:96
	global_load_dwordx4 v[96:99], v[0:1], off offset:128
	global_load_dwordx4 v[100:103], v[0:1], off offset:160
	global_load_dwordx4 v[104:107], v[0:1], off offset:192
	global_load_dwordx4 v[108:111], v[0:1], off offset:224
	v_mov_b32_e32 v15, v189
	v_mov_b32_e32 v0, v189
	v_mov_b32_e32 v1, v189
	v_mov_b32_e32 v2, v189
	v_mov_b32_e32 v3, v189
	v_mov_b32_e32 v4, v189
	v_mov_b32_e32 v5, v189
	v_mov_b32_e32 v6, v189
	v_mov_b32_e32 v7, v189
	v_mov_b32_e32 v8, v189
	v_mov_b32_e32 v9, v189
	v_mov_b32_e32 v10, v189
	v_mov_b32_e32 v11, v189
	v_mov_b32_e32 v12, v189
	v_mov_b32_e32 v13, v189
	s_waitcnt vmcnt(0)
	v_mov_b64_e32 v[30:31], v[14:15]
	v_mov_b64_e32 v[46:47], v[14:15]
	v_mov_b64_e32 v[62:63], v[14:15]
	s_mov_b32 s78, 0
	v_lshl_add_u64 v[152:153], vcc, 0, v[188:189]
	v_lshl_add_u64 v[154:155], s[2:3], 0, v[198:199]
	v_add_u32_e32 v147, s76, v167
	v_add_u32_e32 v149, s76, v168
	v_mov_b32_e32 v172, 0xf149f2ca
	v_mov_b32_e32 v171, 0
	v_mov_b64_e32 v[28:29], v[12:13]
	v_mov_b64_e32 v[26:27], v[10:11]
	v_mov_b64_e32 v[24:25], v[8:9]
	v_mov_b64_e32 v[22:23], v[6:7]
	v_mov_b64_e32 v[20:21], v[4:5]
	v_mov_b64_e32 v[18:19], v[2:3]
	v_mov_b64_e32 v[16:17], v[0:1]
	v_mov_b64_e32 v[44:45], v[12:13]
	v_mov_b64_e32 v[42:43], v[10:11]
	v_mov_b64_e32 v[40:41], v[8:9]
	v_mov_b64_e32 v[38:39], v[6:7]
	v_mov_b64_e32 v[36:37], v[4:5]
	v_mov_b64_e32 v[34:35], v[2:3]
	v_mov_b64_e32 v[32:33], v[0:1]
	v_mov_b64_e32 v[60:61], v[12:13]
	v_mov_b64_e32 v[58:59], v[10:11]
	v_mov_b64_e32 v[56:57], v[8:9]
	v_mov_b64_e32 v[54:55], v[6:7]
	v_mov_b64_e32 v[52:53], v[4:5]
	v_mov_b64_e32 v[50:51], v[2:3]
	v_mov_b64_e32 v[48:49], v[0:1]
	s_mov_b32 s94, s68
.LBB0_1134:
	s_waitcnt vmcnt(8)
	ds_read_b128 v[112:115], v196
	ds_read_b128 v[116:119], v197
	ds_read_b128 v[120:123], v196 offset:2048
	ds_read_b128 v[124:127], v197 offset:2048
	ds_read_b128 v[128:131], v196 offset:4096
	ds_read_b128 v[132:135], v197 offset:4096
	ds_read_b128 v[136:139], v196 offset:6144
	ds_read_b128 v[140:143], v197 offset:6144
	s_waitcnt lgkmcnt(0)
	v_mfma_f32_32x32x16_bf16 v[64:79], v[112:115], v[80:83], 0
	s_cmp_gt_u32 s81, 3
	s_cselect_b64 s[2:3], -1, 0
	s_and_b64 vcc, exec, s[2:3]
	v_mfma_f32_32x32x16_bf16 v[64:79], v[116:119], v[84:87], v[64:79]
	v_mfma_f32_32x32x16_bf16 v[64:79], v[120:123], v[88:91], v[64:79]
	v_mfma_f32_32x32x16_bf16 v[64:79], v[124:127], v[92:95], v[64:79]
	v_mfma_f32_32x32x16_bf16 v[64:79], v[128:131], v[96:99], v[64:79]
	v_mfma_f32_32x32x16_bf16 v[64:79], v[132:135], v[100:103], v[64:79]
	v_mfma_f32_32x32x16_bf16 v[64:79], v[136:139], v[104:107], v[64:79]
	v_mfma_f32_32x32x16_bf16 v[64:79], v[140:143], v[108:111], v[64:79]
	s_cbranch_vccnz .LBB0_1136
	v_ashrrev_i32_e32 v116, 31, v149
	v_mov_b64_e32 v[112:113], s[84:85]
	v_mad_u64_u32 v[114:115], s[0:1], s74, v149, v[112:113]
	v_mul_lo_u32 v117, s75, v149
	v_mul_lo_u32 v116, s74, v116
	v_add3_u32 v115, v117, v115, v116
	v_lshlrev_b64 v[114:115], 8, v[114:115]
	v_lshl_add_u64 v[114:115], v[154:155], 0, v[114:115]
	s_mov_b32 m0, s90
	v_lshl_add_u64 v[116:117], v[114:115], 0, s[96:97]
	global_load_lds_dwordx4 v[114:115], off
	s_add_i32 m0, s90, 0x400
	v_lshl_add_u64 v[118:119], v[114:115], 0, 64
	global_load_lds_dwordx4 v[116:117], off
	s_add_i32 m0, s90, 0x800
	s_nop 0
	global_load_lds_dwordx4 v[118:119], off
	v_lshl_add_u64 v[118:119], v[116:117], 0, 64
	s_add_i32 m0, s90, 0xc00
	s_nop 0
	global_load_lds_dwordx4 v[118:119], off
	v_lshl_add_u64 v[118:119], v[114:115], 0, s[88:89]
	s_add_i32 m0, s90, 0x1000
	v_lshl_add_u64 v[114:115], v[114:115], 0, s[100:101]
	global_load_lds_dwordx4 v[118:119], off
	v_lshl_add_u64 v[118:119], v[116:117], 0, s[88:89]
	s_add_i32 m0, s90, 0x1400
	s_nop 0
	global_load_lds_dwordx4 v[118:119], off
	s_add_i32 m0, s90, 0x1800
	s_nop 0
	global_load_lds_dwordx4 v[114:115], off
	v_lshl_add_u64 v[114:115], v[116:117], 0, s[100:101]
	s_add_i32 m0, s90, 0x1c00
	s_nop 0
	global_load_lds_dwordx4 v[114:115], off

.LBB0_1143:
	s_andn2_b64 vcc, exec, s[0:1]
	s_cbranch_vccnz .LBB0_1145
	s_waitcnt vmcnt(8)
.LBB0_1145:
	v_add_f32_e32 v73, v73, v74
	v_fmac_f32_e32 v73, v171, v72
	v_add_u32_e32 v72, 0x2000, v166
	ds_read_b64_tr_b16 v[180:181], v72 offset:0
	ds_read_b64_tr_b16 v[182:183], v72 offset:0+512
	ds_read_b64_tr_b16 v[176:177], v72 offset:0+1024
	ds_read_b64_tr_b16 v[178:179], v72 offset:0+1536
	ds_read_b64_tr_b16 v[172:173], v72 offset:0+2048
	ds_read_b64_tr_b16 v[174:175], v72 offset:0+2560
	ds_read_b64_tr_b16 v[74:75], v72 offset:0+3072
	ds_read_b64_tr_b16 v[76:77], v72 offset:0+3584
	s_waitcnt lgkmcnt(0)
	s_add_i32 s81, s81, 1
	v_mfma_f32_32x32x16_bf16 v[48:63], v[180:183], v[64:67], v[48:63]
	s_xor_b32 s78, s78, 1
	v_add_u32_e32 v147, 32, v147
	s_andn2_b64 vcc, exec, s[2:3]
	v_mfma_f32_32x32x16_bf16 v[32:47], v[172:175], v[64:67], v[32:47]
	v_mfma_f32_32x32x16_bf16 v[48:63], v[176:179], v[68:71], v[48:63]
	v_mfma_f32_32x32x16_bf16 v[32:47], v[74:77], v[68:71], v[32:47]
	ds_read_b64_tr_b16 v[180:181], v72 offset:0x1000
	ds_read_b64_tr_b16 v[182:183], v72 offset:0x1000+512
	ds_read_b64_tr_b16 v[176:177], v72 offset:0x1000+1024
	ds_read_b64_tr_b16 v[178:179], v72 offset:0x1000+1536
	ds_read_b64_tr_b16 v[172:173], v72 offset:0x1000+2048
	ds_read_b64_tr_b16 v[174:175], v72 offset:0x1000+2560
	ds_read_b64_tr_b16 v[74:75], v72 offset:0x1000+3072
	ds_read_b64_tr_b16 v[76:77], v72 offset:0x1000+3584
	s_waitcnt lgkmcnt(0)
	s_nop 0
	v_mfma_f32_32x32x16_bf16 v[16:31], v[180:183], v[64:67], v[16:31]
	v_mfma_f32_32x32x16_bf16 v[0:15], v[172:175], v[64:67], v[0:15]
	v_mfma_f32_32x32x16_bf16 v[16:31], v[176:179], v[68:71], v[16:31]
	v_mfma_f32_32x32x16_bf16 v[0:15], v[74:77], v[68:71], v[0:15]
	s_cbranch_vccz .LBB0_1148
	v_mov_b32_e32 v171, v73
	v_mov_b32_e32 v172, v145
	v_ashrrev_i32_e32 v116, 31, v149
	v_mov_b64_e32 v[112:113], s[84:85]
	v_mad_u64_u32 v[114:115], s[0:1], s74, v149, v[112:113]
	v_mul_lo_u32 v117, s75, v149
	v_mul_lo_u32 v116, s74, v116
	v_add3_u32 v115, v117, v115, v116
	v_lshlrev_b64 v[114:115], 8, v[114:115]
	v_lshl_add_u64 v[114:115], v[152:153], 0, v[114:115]
	s_add_i32 m0, s90, 0x2000
	v_lshl_add_u64 v[116:117], v[114:115], 0, s[96:97]
	global_load_lds_dwordx4 v[114:115], off
	s_add_i32 m0, s90, 0x2400
	v_lshl_add_u64 v[118:119], v[114:115], 0, 64
	global_load_lds_dwordx4 v[116:117], off
	s_add_i32 m0, s90, 0x2800
	s_nop 0
	global_load_lds_dwordx4 v[118:119], off
	v_lshl_add_u64 v[118:119], v[116:117], 0, 64
	s_add_i32 m0, s90, 0x2c00
	s_nop 0
	global_load_lds_dwordx4 v[118:119], off
	v_lshl_add_u64 v[118:119], v[114:115], 0, s[88:89]
	s_add_i32 m0, s90, 0x3000
	v_lshl_add_u64 v[114:115], v[114:115], 0, s[100:101]
	global_load_lds_dwordx4 v[118:119], off
	v_lshl_add_u64 v[118:119], v[116:117], 0, s[88:89]
	s_add_i32 m0, s90, 0x3400
	s_nop 0
	global_load_lds_dwordx4 v[118:119], off
	s_add_i32 m0, s90, 0x3800
	s_nop 0
	global_load_lds_dwordx4 v[114:115], off
	v_lshl_add_u64 v[114:115], v[116:117], 0, s[100:101]
	s_add_i32 m0, s90, 0x3c00
	s_nop 0
	global_load_lds_dwordx4 v[114:115], off
	v_add_u32_e32 v149, 32, v149
	s_branch .LBB0_1134
